# attention: mask-free copy of the compute block for key blocks below the wave diagonal
# speedup vs baseline: 1.0887x; 1.0004x over previous
; __device__ void sbattn_item(const Params& p, int l, int item, unsigned char* ldsraw) {
;     ...
;     {
;       const int key = tid >> 3, ch = tid & 7;
;       const u16* src = proj + (tokb + kb * 64 + key) * INW + h * 64 + ch * 8;
;       const uint4 kv = *(const uint4*)(src + SBK);
;       const uint4 vv = *(const uint4*)(src + SBV);
;       *(uint4*)(Ks + key * KLD + ch * 8) = kv;
;       const u32 w[4] = {vv.x, vv.y, vv.z, vv.w};
; #pragma unroll
;       for (int i = 0; i < 4; ++i) {
;         Vt[(ch * 8 + 2 * i) * KLD + key] = (u16)(w[i] & 0xffffu);
;         Vt[(ch * 8 + 2 * i + 1) * KLD + key] = (u16)(w[i] >> 16);
;       }
;     }
;     __syncthreads();
;     if (kb > kb_diag) continue;
;     f32x4 st[4];
; #pragma unroll
;     for (int f = 0; f < 4; ++f) {
;       st[f] = (f32x4){0.f, 0.f, 0.f, 0.f};
; #pragma unroll
;       for (int ks = 0; ks < 2; ++ks) {
;         const bf16x8 ak = *(const bf16x8*)(Ks + (f * 16 + l15) * KLD + ks * 32 + g4 * 8);
;         st[f] = __builtin_amdgcn_mfma_f32_16x16x32_bf16(ak, bq[ks], st[f], 0, 0, 0);
;       }
;     }
;     float e0[4][4];
;     bf16x8 lb[2];
;     const bool diag = (kb == kb_diag);
; #pragma unroll
;     for (int f = 0; f < 4; ++f)
; #pragma unroll
;       for (int j = 0; j < 4; ++j) {
;         const float t = st[f][j] * SC;
;         float lv = -(fmaxf(t, 0.f) + __builtin_amdgcn_logf(1.f + __builtin_amdgcn_exp2f(-fabsf(t))));
;         e0[f][j] = t + lv;
;         if (diag) { const int key = kb * 64 + 16 * f + 4 * g4 + j; if (key >= qi) lv = 0.f; }
;         lb[f >> 1][(f & 1) * 4 + j] = (short)f2bf(lv);
.LBB0_507:
	v_lshl_add_u64 v[34:35], s[98:99], 0, v[56:57]
	v_mad_u64_u32 v[38:39], s[0:1], v34, s83, v[58:59]
	v_mad_i32_i24 v39, v35, s83, v39
	global_load_dwordx4 v[34:37], v[38:39], off offset:768
	s_nop 0
	global_load_dwordx4 v[38:41], v[38:39], off offset:1536
	v_cmp_le_i32_e32 vcc, s78, v61
	s_waitcnt vmcnt(1)
	ds_write_b128 v63, v[34:37]
	s_waitcnt vmcnt(0)
	ds_write_b16 v65, v38 offset:9216
	ds_write_b16_d16_hi v66, v38 offset:9360
	ds_write_b16 v65, v39 offset:9504
	ds_write_b16_d16_hi v66, v39 offset:9648
	ds_write_b16 v65, v40 offset:9792
	ds_write_b16_d16_hi v66, v40 offset:9936
	ds_write_b16 v65, v41 offset:10080
	ds_write_b16_d16_hi v66, v41 offset:10224
	s_waitcnt lgkmcnt(0)
	s_barrier
	s_and_saveexec_b64 s[86:87], vcc
	s_cbranch_execz .LBB0_509
	v_readfirstlane_b32 s0, v61
	s_nop 3
	s_cmp_eq_u32 s78, s0
	s_cbranch_scc0 .Lattn_nodiag
	v_add_u32_e32 v33, v64, v67
	ds_read_b128 v[34:37], v33
	ds_read_b128 v[38:41], v33 offset:64
	ds_read_b128 v[42:45], v33 offset:2304
	ds_read_b128 v[46:49], v33 offset:2368
	s_mov_b64 s[56:57], s[44:45]
	s_mov_b32 s44, 0x3e38aa3b
	s_waitcnt lgkmcnt(3)
	v_mfma_f32_16x16x32_bf16 v[34:37], v[34:37], v[24:27], 0
	v_cmp_lt_i32_e64 s[0:1], v70, v54
	v_cmp_eq_u32_e32 vcc, s78, v61
	s_mov_b32 s45, 0x7060302
	s_waitcnt lgkmcnt(1)
	v_mfma_f32_16x16x32_bf16 v[42:45], v[42:45], v[24:27], 0
	s_mov_b64 s[82:83], s[76:77]
	s_mov_b64 s[76:77], s[4:5]
	s_mov_b64 s[4:5], s[88:89]
	v_mfma_f32_16x16x32_bf16 v[34:37], v[38:41], v[28:31], v[34:37]
	ds_read_b128 v[38:41], v33 offset:4608
	ds_read_b128 v[72:75], v33 offset:4672
	s_mov_b64 s[88:89], s[84:85]
	s_mov_b64 s[84:85], s[46:47]
	s_waitcnt lgkmcnt(2)
	v_mfma_f32_16x16x32_bf16 v[44:47], v[46:49], v[28:31], v[42:45]
	ds_read_b128 v[48:51], v33 offset:6912
	ds_read_b128 v[76:79], v33 offset:6976
	v_mul_f32_e32 v33, 0x3e38aa3b, v34
	v_exp_f32_e64 v42, -|v33|
	s_waitcnt lgkmcnt(3)
	v_mfma_f32_16x16x32_bf16 v[38:41], v[38:41], v[24:27], 0
	v_max_f32_e32 v33, 0, v33
	v_mul_f32_e32 v80, 0x3e38aa3b, v35
	v_mul_f32_e32 v81, 0x3e38aa3b, v36
	s_waitcnt lgkmcnt(2)
	v_mfma_f32_16x16x32_bf16 v[72:75], v[72:75], v[28:31], v[38:41]
	s_mov_b64 s[46:47], s[36:37]
	s_mov_b64 s[58:59], s[34:35]
	v_readlane_b32 s48, v161, 24
	v_add_f32_e32 v38, 1.0, v42
	v_log_f32_e32 v42, v38
	s_waitcnt lgkmcnt(1)
	v_mfma_f32_16x16x32_bf16 v[38:41], v[48:51], v[24:27], 0
	v_exp_f32_e64 v48, -|v80|
	s_mov_b32 s52, s48
	v_add_f32_e32 v33, v33, v42
	v_fma_f32 v82, v34, s44, -v33
	v_cndmask_b32_e64 v34, 0, -v33, s[0:1]
	v_cndmask_b32_e64 v33, -v33, v34, vcc
	v_exp_f32_e64 v34, -|v81|
	s_waitcnt lgkmcnt(0)
	v_mfma_f32_16x16x32_bf16 v[40:43], v[76:79], v[28:31], v[38:41]
	v_bfe_u32 v49, v33, 16, 1
	v_add3_u32 v33, v33, v49, s96
	v_add_f32_e32 v34, 1.0, v34
	v_add_f32_e32 v38, 1.0, v48
	v_log_f32_e32 v38, v38
	v_log_f32_e32 v39, v34
	v_max_f32_e32 v48, 0, v80
	v_max_f32_e32 v49, 0, v81
	v_or_b32_e32 v34, 2, v70
	v_pk_add_f32 v[38:39], v[48:49], v[38:39]
	v_cmp_lt_i32_e64 s[8:9], v34, v55
	v_fma_f32 v80, v35, s44, -v38
	v_fma_f32 v81, v36, s44, -v39
	v_cndmask_b32_e64 v34, 0, -v39, s[8:9]
	v_or_b32_e32 v35, 1, v70
	v_cndmask_b32_e64 v36, -v39, v34, vcc
	v_mul_f32_e32 v39, 0x3e38aa3b, v37
	v_mul_f32_e32 v49, 0x3e38aa3b, v44
	v_cmp_lt_i32_e64 s[10:11], v35, v54
	v_exp_f32_e64 v48, -|v39|
	v_exp_f32_e64 v50, -|v49|
	v_cndmask_b32_e64 v35, 0, -v38, s[10:11]
	v_cndmask_b32_e64 v35, -v38, v35, vcc
	v_and_b32_sdwa v34, v35, v93 dst_sel:DWORD dst_unused:UNUSED_PAD src0_sel:WORD_1 src1_sel:DWORD
	v_add3_u32 v51, v35, v34, s96
	v_add_f32_e32 v34, 1.0, v48
	v_add_f32_e32 v35, 1.0, v50
	v_log_f32_e32 v34, v34
	v_log_f32_e32 v35, v35
	v_and_b32_sdwa v38, v36, v93 dst_sel:DWORD dst_unused:UNUSED_PAD src0_sel:WORD_1 src1_sel:DWORD
	v_add3_u32 v48, v36, v38, s96
	v_max_f32_e32 v38, 0, v39
	v_max_f32_e32 v39, 0, v49
	v_pk_add_f32 v[34:35], v[38:39], v[34:35]
	v_mul_f32_e32 v38, 0x3e38aa3b, v45
	v_fma_f32 v83, v37, s44, -v34
	v_or_b32_e32 v37, 3, v70
	v_fma_f32 v84, v44, s44, -v35
	v_mul_f32_e32 v44, 0x3e38aa3b, v46
	v_or_b32_e32 v36, 16, v70
	v_cmp_lt_i32_e64 s[14:15], v37, v54
	v_exp_f32_e64 v39, -|v38|
	v_exp_f32_e64 v49, -|v44|
	v_cmp_lt_i32_e64 s[12:13], v36, v55
	v_cndmask_b32_e64 v37, 0, -v34, s[14:15]
	v_cndmask_b32_e64 v34, -v34, v37, vcc
	v_cndmask_b32_e64 v36, 0, -v35, s[12:13]
	v_cndmask_b32_e64 v36, -v35, v36, vcc
	v_and_b32_sdwa v35, v34, v93 dst_sel:DWORD dst_unused:UNUSED_PAD src0_sel:WORD_1 src1_sel:DWORD
	v_add3_u32 v50, v34, v35, s96
	v_add_f32_e32 v34, 1.0, v39
	v_add_f32_e32 v35, 1.0, v49
	v_log_f32_e32 v34, v34
	v_log_f32_e32 v35, v35
	v_and_b32_sdwa v37, v36, v93 dst_sel:DWORD dst_unused:UNUSED_PAD src0_sel:WORD_1 src1_sel:DWORD
	v_add3_u32 v39, v36, v37, s96
	v_max_f32_e32 v36, 0, v38
	v_max_f32_e32 v37, 0, v44
	v_pk_add_f32 v[34:35], v[36:37], v[34:35]
	v_or_b32_e32 v37, 17, v70
	v_cmp_lt_i32_e64 s[18:19], v37, v54
	v_fma_f32 v85, v45, s44, -v34
	v_or_b32_e32 v36, 18, v70
	v_cndmask_b32_e64 v37, 0, -v34, s[18:19]
	v_cndmask_b32_e64 v34, -v34, v37, vcc
	v_mul_f32_e32 v37, 0x3e38aa3b, v47
	v_exp_f32_e64 v38, -|v37|
	v_cmp_lt_i32_e64 s[16:17], v36, v55
	v_fma_f32 v86, v46, s44, -v35
	v_and_b32_sdwa v44, v34, v93 dst_sel:DWORD dst_unused:UNUSED_PAD src0_sel:WORD_1 src1_sel:DWORD
	v_add_f32_e32 v38, 1.0, v38
	v_cndmask_b32_e64 v36, 0, -v35, s[16:17]
	v_log_f32_e32 v38, v38
	v_cndmask_b32_e64 v35, -v35, v36, vcc
	v_and_b32_sdwa v36, v35, v93 dst_sel:DWORD dst_unused:UNUSED_PAD src0_sel:WORD_1 src1_sel:DWORD
	v_add3_u32 v45, v35, v36, s96
	v_max_f32_e32 v35, 0, v37
	v_add_u32_e32 v36, 19, v70
	v_add_f32_e32 v35, v35, v38
	v_cmp_lt_i32_e64 s[22:23], v36, v54
	v_add3_u32 v34, v34, v44, s96
; __device__ void sbattn_item(const Params& p, int l, int item, unsigned char* ldsraw) {
;     ...
;     const f32x4 cv = (f32x4){carry, carry, carry, carry};
;     f32x4 tot = __builtin_amdgcn_mfma_f32_16x16x32_bf16(ONES, lb[0], cv, 0, 0, 0);
;     tot = __builtin_amdgcn_mfma_f32_16x16x32_bf16(ONES, lb[1], tot, 0, 0, 0);
;     bf16x8 wb[2];
; #pragma unroll
;     for (int f = 0; f < 4; ++f) {
;       f32x4 bt;
;       if (f == 0) { bt = __builtin_amdgcn_mfma_f32_16x16x32_bf16(P0, lb[0], cv, 0, 0, 0); bt = __builtin_amdgcn_mfma_f32_16x16x32_bf16(ONES, lb[1], bt, 0, 0, 0); }
;       else if (f == 1) { bt = __builtin_amdgcn_mfma_f32_16x16x32_bf16(P1, lb[0], cv, 0, 0, 0); bt = __builtin_amdgcn_mfma_f32_16x16x32_bf16(ONES, lb[1], bt, 0, 0, 0); }
;       else if (f == 2) bt = __builtin_amdgcn_mfma_f32_16x16x32_bf16(P0, lb[1], cv, 0, 0, 0);
;       else bt = __builtin_amdgcn_mfma_f32_16x16x32_bf16(P1, lb[1], cv, 0, 0, 0);
; #pragma unroll
;       for (int j = 0; j < 4; ++j) {
;         float w = __builtin_amdgcn_exp2f(e0[f][j] + bt[j]);
;         if (diag) { const int key = kb * 64 + 16 * f + 4 * g4 + j; if (key >= qi) w = 0.f; }
;         wb[f >> 1][(f & 1) * 4 + j] = (short)f2bf(w);
;       }
	v_fma_f32 v87, v47, s44, -v35
	v_cndmask_b32_e64 v36, 0, -v35, s[22:23]
	v_cndmask_b32_e64 v35, -v35, v36, vcc
	v_mul_f32_e32 v46, 0x3e38aa3b, v72
	v_bfe_u32 v36, v35, 16, 1
	v_perm_b32 v38, v34, v39, s45
	v_exp_f32_e64 v34, -|v46|
	v_mul_f32_e32 v47, 0x3e38aa3b, v73
	v_add3_u32 v44, v35, v36, s96
	v_exp_f32_e64 v35, -|v47|
	v_perm_b32 v36, v51, v33, s45
	v_add_f32_e32 v33, 1.0, v34
	v_log_f32_e32 v34, v33
	v_add_f32_e32 v33, 1.0, v35
	v_log_f32_e32 v35, v33
	v_perm_b32 v39, v44, v45, s45
	v_max_f32_e32 v44, 0, v46
	v_max_f32_e32 v45, 0, v47
	v_mul_f32_e32 v46, 0x3e38aa3b, v74
	v_pk_add_f32 v[34:35], v[44:45], v[34:35]
	v_exp_f32_e64 v45, -|v46|
	v_mul_f32_e32 v47, 0x3e38aa3b, v75
	v_perm_b32 v37, v50, v48, s45
	v_or_b32_e32 v44, 32, v70
	v_exp_f32_e64 v48, -|v47|
	v_cmp_lt_i32_e64 s[26:27], v44, v54
	v_fma_f32 v103, v72, s44, -v34
	v_or_b32_e32 v33, 33, v70
	v_cndmask_b32_e64 v44, 0, -v34, s[26:27]
	v_cndmask_b32_e64 v49, -v34, v44, vcc
	v_add_f32_e32 v34, 1.0, v45
	v_log_f32_e32 v44, v34
	v_add_f32_e32 v34, 1.0, v48
	v_log_f32_e32 v45, v34
	v_cmp_lt_i32_e64 s[24:25], v33, v55
	v_fma_f32 v104, v73, s44, -v35
	v_max_f32_e32 v34, 0, v46
	v_cndmask_b32_e64 v33, 0, -v35, s[24:25]
	v_cndmask_b32_e64 v48, -v35, v33, vcc
	v_max_f32_e32 v35, 0, v47
	v_mul_f32_e32 v46, 0x3e38aa3b, v40
	v_pk_add_f32 v[34:35], v[34:35], v[44:45]
	v_exp_f32_e64 v45, -|v46|
	v_mul_f32_e32 v47, 0x3e38aa3b, v41
	v_or_b32_e32 v44, 34, v70
	v_exp_f32_e64 v50, -|v47|
	v_cmp_lt_i32_e64 s[30:31], v44, v54
	v_fma_f32 v105, v74, s44, -v34
	v_or_b32_e32 v33, 35, v70
	v_cndmask_b32_e64 v44, 0, -v34, s[30:31]
	v_cndmask_b32_e64 v51, -v34, v44, vcc
	v_add_f32_e32 v34, 1.0, v45
	v_log_f32_e32 v44, v34
	v_add_f32_e32 v34, 1.0, v50
	v_log_f32_e32 v45, v34
	v_cmp_lt_i32_e64 s[28:29], v33, v55
	v_fma_f32 v106, v75, s44, -v35
	v_max_f32_e32 v34, 0, v46
	v_cndmask_b32_e64 v33, 0, -v35, s[28:29]
	v_cndmask_b32_e64 v50, -v35, v33, vcc
	v_max_f32_e32 v35, 0, v47
	v_pk_add_f32 v[76:77], v[34:35], v[44:45]
	v_mul_f32_e32 v45, 0x3e38aa3b, v43
	v_fma_f32 v107, v40, s44, -v76
	v_mul_f32_e32 v40, 0x3e38aa3b, v42
	v_exp_f32_e64 v35, -|v40|
	v_exp_f32_e64 v44, -|v45|
	v_or_b32_e32 v34, 48, v70
	v_cmp_lt_i32_e64 s[36:37], v34, v54
	v_or_b32_e32 v33, 49, v70
	v_cmp_lt_i32_e64 s[34:35], v33, v55
	v_cndmask_b32_e64 v34, 0, -v76, s[36:37]
	v_cndmask_b32_e64 v46, -v76, v34, vcc
	v_add_f32_e32 v34, 1.0, v35
	v_add_f32_e32 v35, 1.0, v44
	v_log_f32_e32 v34, v34
	v_log_f32_e32 v35, v35
	v_max_f32_e32 v44, 0, v40
	v_max_f32_e32 v45, 0, v45
	v_cndmask_b32_e64 v33, 0, -v77, s[34:35]
	v_pk_add_f32 v[78:79], v[44:45], v[34:35]
	v_or_b32_e32 v34, 50, v70
	v_cndmask_b32_e64 v47, -v77, v33, vcc
	v_or_b32_e32 v33, 51, v70
	v_cmp_lt_i32_e64 s[40:41], v34, v54
	v_cmp_lt_i32_e64 s[38:39], v33, v55
	v_bfe_u32 v75, v50, 16, 1
	v_cndmask_b32_e64 v34, 0, -v78, s[40:41]
	v_bfe_u32 v76, v51, 16, 1
	v_bfe_u32 v108, v48, 16, 1
	v_bfe_u32 v109, v49, 16, 1
	s_mov_b32 s53, s48
	v_cndmask_b32_e64 v33, 0, -v79, s[38:39]
	v_cndmask_b32_e64 v40, -v78, v34, vcc
	v_add3_u32 v109, v49, v109, s96
	v_add3_u32 v108, v48, v108, s96
	v_add3_u32 v76, v51, v76, s96
	v_add3_u32 v110, v50, v75, s96
	s_mov_b32 s54, s48
	s_mov_b32 s55, s48
	v_mov_b64_e32 v[48:49], s[52:53]
	v_cndmask_b32_e64 v44, -v79, v33, vcc
	v_mov_b32_e32 v33, v32
	v_mov_b32_e32 v34, v32
	v_mov_b32_e32 v35, v32
	v_bfe_u32 v72, v40, 16, 1
	v_bfe_u32 v73, v47, 16, 1
	v_bfe_u32 v74, v46, 16, 1
	v_mov_b64_e32 v[50:51], s[54:55]
	v_add3_u32 v46, v46, v74, s96
	v_add3_u32 v111, v47, v73, s96
	v_add3_u32 v40, v40, v72, s96
	v_mfma_f32_16x16x32_bf16 v[72:75], v[4:7], v[36:39], v[32:35]
	v_bfe_u32 v45, v44, 16, 1
	v_add3_u32 v44, v44, v45, s96
	v_perm_b32 v47, v44, v40, s45
	v_perm_b32 v46, v111, v46, s45
	v_perm_b32 v45, v110, v76, s45
	v_perm_b32 v44, v108, v109, s45
	v_fma_f32 v76, v42, s44, -v78
	v_readlane_b32 s49, v161, 25
	v_mfma_f32_16x16x32_bf16 v[72:75], v[48:51], v[44:47], v[72:75]
	v_readlane_b32 s50, v161, 26
	v_readlane_b32 s51, v161, 27
	v_writelane_b32 v161, s48, 24
	v_readlane_b32 s60, v160, 9
	v_readlane_b32 s61, v160, 10
	s_nop 2
	v_add_f32_e32 v40, v82, v72
	v_exp_f32_e32 v40, v40
	v_fma_f32 v72, v41, s44, -v77
	v_add_f32_e32 v42, v80, v73
	v_exp_f32_e32 v42, v42
	v_cndmask_b32_e64 v41, 0, v40, s[0:1]
	v_cndmask_b32_e32 v40, v40, v41, vcc
	v_bfe_u32 v41, v40, 16, 1
	v_add3_u32 v78, v40, v41, s96
	v_add_f32_e32 v41, v81, v74
	v_exp_f32_e32 v41, v41
	v_cndmask_b32_e64 v40, 0, v42, s[10:11]
	v_cndmask_b32_e32 v40, v42, v40, vcc
	v_bfe_u32 v42, v40, 16, 1
	v_fma_f32 v77, v43, s44, -v79
	v_add3_u32 v79, v40, v42, s96
	v_cndmask_b32_e64 v40, 0, v41, s[8:9]
	v_cndmask_b32_e32 v73, v41, v40, vcc
	v_add_f32_e32 v40, v83, v75
	v_exp_f32_e32 v74, v40
	v_mfma_f32_16x16x32_bf16 v[40:43], v[0:3], v[36:39], v[32:35]
	v_bfe_u32 v75, v73, 16, 1
	v_add3_u32 v80, v73, v75, s96
	v_cndmask_b32_e64 v73, 0, v74, s[14:15]
	v_mfma_f32_16x16x32_bf16 v[40:43], v[48:51], v[44:47], v[40:43]
	v_cndmask_b32_e32 v73, v74, v73, vcc
	v_bfe_u32 v74, v73, 16, 1
	v_add3_u32 v81, v73, v74, s96
	s_mov_b32 s0, 0xffff
	v_writelane_b32 v161, s49, 25
	s_nop 2
	v_add_f32_e32 v40, v84, v40
	v_exp_f32_e32 v40, v40
	v_add_f32_e32 v41, v85, v41
	v_exp_f32_e32 v41, v41
	v_add_f32_e32 v42, v86, v42
	v_cndmask_b32_e64 v73, 0, v40, s[12:13]
	v_cndmask_b32_e32 v40, v40, v73, vcc
	v_bfe_u32 v73, v40, 16, 1
	v_exp_f32_e32 v42, v42
	v_add3_u32 v82, v40, v73, s96
	v_cndmask_b32_e64 v40, 0, v41, s[18:19]
	v_cndmask_b32_e32 v40, v41, v40, vcc
	v_bfe_u32 v41, v40, 16, 1
	v_add3_u32 v83, v40, v41, s96
	v_cndmask_b32_e64 v40, 0, v42, s[16:17]
	v_add_f32_e32 v41, v87, v43
	v_cndmask_b32_e32 v40, v42, v40, vcc
	v_exp_f32_e32 v73, v41
; __device__ void sbattn_item(const Params& p, int l, int item, unsigned char* ldsraw) {
;     ...
; #pragma unroll
;     for (int df = 0; df < 4; ++df)
; #pragma unroll
;       for (int k2 = 0; k2 < 2; ++k2) {
;         const u16* vp = Vt + (df * 16 + l15) * KLD + k2 * 32 + 4 * g4;
;         const uint2 lo = *(const uint2*)(vp);
;         const uint2 hi = *(const uint2*)(vp + 16);
;         bf16x8 av;
;         av[0] = (short)(lo.x & 0xffff); av[1] = (short)(lo.x >> 16); av[2] = (short)(lo.y & 0xffff); av[3] = (short)(lo.y >> 16);
;         av[4] = (short)(hi.x & 0xffff); av[5] = (short)(hi.x >> 16); av[6] = (short)(hi.y & 0xffff); av[7] = (short)(hi.y >> 16);
;         ot[df] = __builtin_amdgcn_mfma_f32_16x16x32_bf16(av, wb[k2], ot[df], 0, 0, 0);
;       }
;     carry = tot[0];
	v_bfe_u32 v41, v40, 16, 1
	v_add3_u32 v74, v40, v41, s96
	v_mfma_f32_16x16x32_bf16 v[40:43], v[4:7], v[44:47], v[32:35]
	v_cndmask_b32_e64 v75, 0, v73, s[22:23]
	v_cndmask_b32_e32 v73, v73, v75, vcc
	v_bfe_u32 v75, v73, 16, 1
	v_add3_u32 v73, v73, v75, s96
	v_writelane_b32 v161, s50, 26
	s_nop 2
	v_add_f32_e32 v40, v103, v40
	v_exp_f32_e32 v40, v40
	v_add_f32_e32 v41, v104, v41
	v_exp_f32_e32 v41, v41
	v_add_f32_e32 v42, v105, v42
	v_cndmask_b32_e64 v75, 0, v40, s[26:27]
	v_cndmask_b32_e32 v40, v40, v75, vcc
	v_bfe_u32 v75, v40, 16, 1
	v_exp_f32_e32 v42, v42
	v_add3_u32 v84, v40, v75, s96
	v_cndmask_b32_e64 v40, 0, v41, s[24:25]
	v_cndmask_b32_e32 v40, v41, v40, vcc
	v_bfe_u32 v41, v40, 16, 1
	v_add3_u32 v85, v40, v41, s96
	v_cndmask_b32_e64 v40, 0, v42, s[30:31]
	v_add_f32_e32 v41, v106, v43
	v_cndmask_b32_e32 v40, v42, v40, vcc
	v_exp_f32_e32 v75, v41
	v_bfe_u32 v41, v40, 16, 1
	v_add3_u32 v86, v40, v41, s96
	v_mfma_f32_16x16x32_bf16 v[40:43], v[0:3], v[44:47], v[32:35]
	v_cndmask_b32_e64 v87, 0, v75, s[28:29]
	v_cndmask_b32_e32 v75, v75, v87, vcc
	v_bfe_u32 v87, v75, 16, 1
	v_add3_u32 v87, v75, v87, s96
	v_mfma_f32_16x16x32_bf16 v[32:35], v[48:51], v[36:39], v[32:35]
	s_nop 2
	v_add_f32_e32 v40, v40, v107
	v_exp_f32_e32 v40, v40
	v_add_f32_e32 v41, v41, v72
	v_exp_f32_e32 v41, v41
	v_add_f32_e32 v42, v42, v76
	v_cndmask_b32_e64 v75, 0, v40, s[36:37]
	v_cndmask_b32_e32 v40, v40, v75, vcc
	v_bfe_u32 v72, v40, 16, 1
	v_add3_u32 v103, v40, v72, s96
	v_cndmask_b32_e64 v40, 0, v41, s[34:35]
	v_exp_f32_e32 v42, v42
	v_cndmask_b32_e32 v40, v41, v40, vcc
	v_bfe_u32 v41, v40, 16, 1
	v_add3_u32 v104, v40, v41, s96
	v_add_f32_e32 v41, v43, v77
	v_cndmask_b32_e64 v40, 0, v42, s[40:41]
	v_exp_f32_e32 v72, v41
	v_cndmask_b32_e32 v40, v42, v40, vcc
	v_bfe_u32 v41, v40, 16, 1
	v_add_u32_e32 v77, 0x2000, v71
	v_add3_u32 v76, v40, v41, s96
	ds_read2_b64 v[40:43], v77 offset0:128 offset1:132
	v_cndmask_b32_e64 v75, 0, v72, s[38:39]
	v_cndmask_b32_e32 v72, v72, v75, vcc
	v_bfe_u32 v75, v72, 16, 1
	v_add3_u32 v105, v72, v75, s96
	v_perm_b32 v39, v73, v74, s45
	ds_read2_b64 v[72:75], v77 offset0:136 offset1:140
	s_waitcnt lgkmcnt(1)
	v_bfi_b32 v42, s0, v42, v42
	v_perm_b32 v38, v83, v82, s45
	v_perm_b32 v37, v81, v80, s45
	v_perm_b32 v36, v79, v78, s45
	s_waitcnt lgkmcnt(0)
	v_bfi_b32 v74, s0, v74, v74
	v_add_u32_e32 v80, 0x2800, v71
	v_mfma_f32_16x16x32_bf16 v[20:23], v[40:43], v[36:39], v[20:23]
	v_perm_b32 v43, v105, v76, s45
	ds_read2_b64 v[76:79], v80 offset0:160 offset1:164
	v_perm_b32 v42, v104, v103, s45
	v_perm_b32 v41, v87, v86, s45
	v_perm_b32 v40, v85, v84, s45
	v_mfma_f32_16x16x32_bf16 v[32:35], v[48:51], v[44:47], v[32:35]
	s_waitcnt lgkmcnt(0)
	v_bfi_b32 v78, s0, v78, v78
	v_writelane_b32 v161, s51, 27
	v_readlane_b32 s62, v160, 11
	v_mfma_f32_16x16x32_bf16 v[20:23], v[72:75], v[40:43], v[20:23]
	ds_read2_b64 v[72:75], v80 offset0:168 offset1:172
	v_add_u32_e32 v80, 0x3000, v71
	v_readlane_b32 s24, v161, 44
	v_mfma_f32_16x16x32_bf16 v[16:19], v[76:79], v[36:39], v[16:19]
	ds_read2_b64 v[76:79], v80 offset0:192 offset1:196
	s_waitcnt lgkmcnt(1)
	v_bfi_b32 v74, s0, v74, v74
	v_readlane_b32 s63, v160, 12
	v_readlane_b32 s64, v160, 13
	v_mfma_f32_16x16x32_bf16 v[16:19], v[72:75], v[40:43], v[16:19]
	ds_read2_b64 v[72:75], v80 offset0:200 offset1:204
	s_waitcnt lgkmcnt(1)
	v_bfi_b32 v78, s0, v78, v78
	v_add_u32_e32 v80, 0x3800, v71
	v_readlane_b32 s65, v160, 14
	v_mfma_f32_16x16x32_bf16 v[12:15], v[76:79], v[36:39], v[12:15]
	s_waitcnt lgkmcnt(0)
	v_bfi_b32 v74, s0, v74, v74
	ds_read2_b64 v[76:79], v80 offset0:224 offset1:228
	v_readlane_b32 s66, v160, 15
	v_mfma_f32_16x16x32_bf16 v[12:15], v[72:75], v[40:43], v[12:15]
	ds_read2_b64 v[72:75], v80 offset0:232 offset1:236
	s_waitcnt lgkmcnt(1)
	v_bfi_b32 v78, s0, v78, v78
	v_readlane_b32 s67, v160, 16
	v_readlane_b32 s68, v160, 17
	v_mfma_f32_16x16x32_bf16 v[8:11], v[76:79], v[36:39], v[8:11]
	s_waitcnt lgkmcnt(0)
	v_bfi_b32 v74, s0, v74, v74
	v_readlane_b32 s69, v160, 18
	v_readlane_b32 s70, v160, 19
	v_mfma_f32_16x16x32_bf16 v[8:11], v[72:75], v[40:43], v[8:11]
	v_readlane_b32 s71, v160, 20
	v_readlane_b32 s72, v160, 21
	v_readlane_b32 s73, v160, 22
	v_readlane_b32 s74, v160, 23
	v_readlane_b32 s75, v160, 24
	v_readlane_b32 s25, v161, 45
	v_readlane_b32 s26, v161, 46
	v_readlane_b32 s27, v161, 47
	s_mov_b64 s[36:37], s[46:47]
	s_mov_b64 s[46:47], s[84:85]
	s_mov_b64 s[84:85], s[88:89]
	s_mov_b64 s[88:89], s[4:5]
	s_mov_b64 s[4:5], s[76:77]
	s_mov_b64 s[76:77], s[82:83]
	s_movk_i32 s83, 0x1920
	s_mov_b32 s82, 0x800000
	s_mov_b64 s[34:35], s[58:59]
	s_movk_i32 s40, 0x1000
	s_movk_i32 s41, 0x180
	s_mov_b64 s[44:45], s[56:57]
	s_branch .LBB0_509
; __device__ void sbattn_item(const Params& p, int l, int item, unsigned char* ldsraw) {
;     ...
;         const bf16x8 ak = *(const bf16x8*)(Ks + (f * 16 + l15) * KLD + ks * 32 + g4 * 8);
;         st[f] = __builtin_amdgcn_mfma_f32_16x16x32_bf16(ak, bq[ks], st[f], 0, 0, 0);
;       }
;     }
;     float e0[4][4];
;     bf16x8 lb[2];
;     const bool diag = (kb == kb_diag);
; #pragma unroll
;     for (int f = 0; f < 4; ++f)
; #pragma unroll
;       for (int j = 0; j < 4; ++j) {
;         const float t = st[f][j] * SC;
;         float lv = -(fmaxf(t, 0.f) + __builtin_amdgcn_logf(1.f + __builtin_amdgcn_exp2f(-fabsf(t))));
;         e0[f][j] = t + lv;
;         if (diag) { const int key = kb * 64 + 16 * f + 4 * g4 + j; if (key >= qi) lv = 0.f; }
;         lb[f >> 1][(f & 1) * 4 + j] = (short)f2bf(lv);
.Lattn_nodiag:
	v_add_u32_e32 v33, v64, v67
	ds_read_b128 v[34:37], v33
	ds_read_b128 v[38:41], v33 offset:64
	ds_read_b128 v[42:45], v33 offset:2304
	ds_read_b128 v[46:49], v33 offset:2368
	s_mov_b64 s[56:57], s[44:45]
	s_mov_b32 s44, 0x3e38aa3b
	s_waitcnt lgkmcnt(3)
	v_mfma_f32_16x16x32_bf16 v[34:37], v[34:37], v[24:27], 0
	s_nop 0
	s_nop 0
	s_mov_b32 s45, 0x7060302
	s_waitcnt lgkmcnt(1)
	v_mfma_f32_16x16x32_bf16 v[42:45], v[42:45], v[24:27], 0
	s_mov_b64 s[82:83], s[76:77]
	s_mov_b64 s[76:77], s[4:5]
	s_mov_b64 s[4:5], s[88:89]
	v_mfma_f32_16x16x32_bf16 v[34:37], v[38:41], v[28:31], v[34:37]
	ds_read_b128 v[38:41], v33 offset:4608
	ds_read_b128 v[72:75], v33 offset:4672
	s_mov_b64 s[88:89], s[84:85]
	s_mov_b64 s[84:85], s[46:47]
	s_waitcnt lgkmcnt(2)
	v_mfma_f32_16x16x32_bf16 v[44:47], v[46:49], v[28:31], v[42:45]
	ds_read_b128 v[48:51], v33 offset:6912
	ds_read_b128 v[76:79], v33 offset:6976
	v_mul_f32_e32 v33, 0x3e38aa3b, v34
	v_exp_f32_e64 v42, -|v33|
	s_waitcnt lgkmcnt(3)
	v_mfma_f32_16x16x32_bf16 v[38:41], v[38:41], v[24:27], 0
	v_max_f32_e32 v33, 0, v33
	v_mul_f32_e32 v80, 0x3e38aa3b, v35
	v_mul_f32_e32 v81, 0x3e38aa3b, v36
	s_waitcnt lgkmcnt(2)
	v_mfma_f32_16x16x32_bf16 v[72:75], v[72:75], v[28:31], v[38:41]
	s_mov_b64 s[46:47], s[36:37]
	s_mov_b64 s[58:59], s[34:35]
	v_readlane_b32 s48, v161, 24
	v_add_f32_e32 v38, 1.0, v42
	v_log_f32_e32 v42, v38
	s_waitcnt lgkmcnt(1)
	v_mfma_f32_16x16x32_bf16 v[38:41], v[48:51], v[24:27], 0
	v_exp_f32_e64 v48, -|v80|
	s_mov_b32 s52, s48
	v_add_f32_e32 v33, v33, v42
	v_fma_f32 v82, v34, s44, -v33
	s_nop 0
	v_xor_b32_e32 v33, 0x80000000, v33
	v_exp_f32_e64 v34, -|v81|
	s_waitcnt lgkmcnt(0)
	v_mfma_f32_16x16x32_bf16 v[40:43], v[76:79], v[28:31], v[38:41]
	v_bfe_u32 v49, v33, 16, 1
	v_add3_u32 v33, v33, v49, s96
	v_add_f32_e32 v34, 1.0, v34
	v_add_f32_e32 v38, 1.0, v48
	v_log_f32_e32 v38, v38
	v_log_f32_e32 v39, v34
	v_max_f32_e32 v48, 0, v80
	v_max_f32_e32 v49, 0, v81
	s_nop 0
	v_pk_add_f32 v[38:39], v[48:49], v[38:39]
	s_nop 0
	v_fma_f32 v80, v35, s44, -v38
	v_fma_f32 v81, v36, s44, -v39
	s_nop 0
	s_nop 0
	v_xor_b32_e32 v36, 0x80000000, v39
	v_mul_f32_e32 v39, 0x3e38aa3b, v37
	v_mul_f32_e32 v49, 0x3e38aa3b, v44
	s_nop 0
	v_exp_f32_e64 v48, -|v39|
	v_exp_f32_e64 v50, -|v49|
	s_nop 0
	v_xor_b32_e32 v35, 0x80000000, v38
	v_and_b32_sdwa v34, v35, v93 dst_sel:DWORD dst_unused:UNUSED_PAD src0_sel:WORD_1 src1_sel:DWORD
	v_add3_u32 v51, v35, v34, s96
	v_add_f32_e32 v34, 1.0, v48
	v_add_f32_e32 v35, 1.0, v50
	v_log_f32_e32 v34, v34
	v_log_f32_e32 v35, v35
	v_and_b32_sdwa v38, v36, v93 dst_sel:DWORD dst_unused:UNUSED_PAD src0_sel:WORD_1 src1_sel:DWORD
	v_add3_u32 v48, v36, v38, s96
	v_max_f32_e32 v38, 0, v39
	v_max_f32_e32 v39, 0, v49
	v_pk_add_f32 v[34:35], v[38:39], v[34:35]
	v_mul_f32_e32 v38, 0x3e38aa3b, v45
	v_fma_f32 v83, v37, s44, -v34
	s_nop 0
	v_fma_f32 v84, v44, s44, -v35
	v_mul_f32_e32 v44, 0x3e38aa3b, v46
	s_nop 0
	s_nop 0
	v_exp_f32_e64 v39, -|v38|
	v_exp_f32_e64 v49, -|v44|
	s_nop 0
	s_nop 0
	v_xor_b32_e32 v34, 0x80000000, v34
	s_nop 0
	v_xor_b32_e32 v36, 0x80000000, v35
	v_and_b32_sdwa v35, v34, v93 dst_sel:DWORD dst_unused:UNUSED_PAD src0_sel:WORD_1 src1_sel:DWORD
	v_add3_u32 v50, v34, v35, s96
	v_add_f32_e32 v34, 1.0, v39
	v_add_f32_e32 v35, 1.0, v49
	v_log_f32_e32 v34, v34
	v_log_f32_e32 v35, v35
	v_and_b32_sdwa v37, v36, v93 dst_sel:DWORD dst_unused:UNUSED_PAD src0_sel:WORD_1 src1_sel:DWORD
	v_add3_u32 v39, v36, v37, s96
	v_max_f32_e32 v36, 0, v38
	v_max_f32_e32 v37, 0, v44
	v_pk_add_f32 v[34:35], v[36:37], v[34:35]
	s_nop 0
	s_nop 0
	v_fma_f32 v85, v45, s44, -v34
	s_nop 0
	s_nop 0
	v_xor_b32_e32 v34, 0x80000000, v34
	v_mul_f32_e32 v37, 0x3e38aa3b, v47
	v_exp_f32_e64 v38, -|v37|
	s_nop 0
	v_fma_f32 v86, v46, s44, -v35
	v_and_b32_sdwa v44, v34, v93 dst_sel:DWORD dst_unused:UNUSED_PAD src0_sel:WORD_1 src1_sel:DWORD
	v_add_f32_e32 v38, 1.0, v38
	s_nop 0
	v_log_f32_e32 v38, v38
	v_xor_b32_e32 v35, 0x80000000, v35
	v_and_b32_sdwa v36, v35, v93 dst_sel:DWORD dst_unused:UNUSED_PAD src0_sel:WORD_1 src1_sel:DWORD
	v_add3_u32 v45, v35, v36, s96
	v_max_f32_e32 v35, 0, v37
	s_nop 0
	v_add_f32_e32 v35, v35, v38
	s_nop 0
	v_add3_u32 v34, v34, v44, s96
	v_fma_f32 v87, v47, s44, -v35
	s_nop 0
	v_xor_b32_e32 v35, 0x80000000, v35
	v_mul_f32_e32 v46, 0x3e38aa3b, v72
	v_bfe_u32 v36, v35, 16, 1
	v_perm_b32 v38, v34, v39, s45
	v_exp_f32_e64 v34, -|v46|
	v_mul_f32_e32 v47, 0x3e38aa3b, v73
	v_add3_u32 v44, v35, v36, s96
	v_exp_f32_e64 v35, -|v47|
	v_perm_b32 v36, v51, v33, s45
	v_add_f32_e32 v33, 1.0, v34
	v_log_f32_e32 v34, v33
	v_add_f32_e32 v33, 1.0, v35
	v_log_f32_e32 v35, v33
	v_perm_b32 v39, v44, v45, s45
	v_max_f32_e32 v44, 0, v46
	v_max_f32_e32 v45, 0, v47
	v_mul_f32_e32 v46, 0x3e38aa3b, v74
	v_pk_add_f32 v[34:35], v[44:45], v[34:35]
	v_exp_f32_e64 v45, -|v46|
	v_mul_f32_e32 v47, 0x3e38aa3b, v75
	v_perm_b32 v37, v50, v48, s45
	s_nop 0
	v_exp_f32_e64 v48, -|v47|
	s_nop 0
	v_fma_f32 v103, v72, s44, -v34
	s_nop 0
	s_nop 0
	v_xor_b32_e32 v49, 0x80000000, v34
	v_add_f32_e32 v34, 1.0, v45
	v_log_f32_e32 v44, v34
	v_add_f32_e32 v34, 1.0, v48
	v_log_f32_e32 v45, v34
	s_nop 0
	v_fma_f32 v104, v73, s44, -v35
	v_max_f32_e32 v34, 0, v46
	s_nop 0
	v_xor_b32_e32 v48, 0x80000000, v35
	v_max_f32_e32 v35, 0, v47
	v_mul_f32_e32 v46, 0x3e38aa3b, v40
	v_pk_add_f32 v[34:35], v[34:35], v[44:45]
	v_exp_f32_e64 v45, -|v46|
	v_mul_f32_e32 v47, 0x3e38aa3b, v41
	s_nop 0
	v_exp_f32_e64 v50, -|v47|
	s_nop 0
	v_fma_f32 v105, v74, s44, -v34
	s_nop 0
	s_nop 0
	v_xor_b32_e32 v51, 0x80000000, v34
	v_add_f32_e32 v34, 1.0, v45
	v_log_f32_e32 v44, v34
	v_add_f32_e32 v34, 1.0, v50
	v_log_f32_e32 v45, v34
	s_nop 0
	v_fma_f32 v106, v75, s44, -v35
; __device__ void sbattn_item(const Params& p, int l, int item, unsigned char* ldsraw) {
;     ...
;         float lv = -(fmaxf(t, 0.f) + __builtin_amdgcn_logf(1.f + __builtin_amdgcn_exp2f(-fabsf(t))));
;         e0[f][j] = t + lv;
;         if (diag) { const int key = kb * 64 + 16 * f + 4 * g4 + j; if (key >= qi) lv = 0.f; }
;         lb[f >> 1][(f & 1) * 4 + j] = (short)f2bf(lv);
;       }
;     const f32x4 cv = (f32x4){carry, carry, carry, carry};
;     f32x4 tot = __builtin_amdgcn_mfma_f32_16x16x32_bf16(ONES, lb[0], cv, 0, 0, 0);
;     tot = __builtin_amdgcn_mfma_f32_16x16x32_bf16(ONES, lb[1], tot, 0, 0, 0);
;     bf16x8 wb[2];
; #pragma unroll
;     for (int f = 0; f < 4; ++f) {
;       f32x4 bt;
;       if (f == 0) { bt = __builtin_amdgcn_mfma_f32_16x16x32_bf16(P0, lb[0], cv, 0, 0, 0); bt = __builtin_amdgcn_mfma_f32_16x16x32_bf16(ONES, lb[1], bt, 0, 0, 0); }
;       else if (f == 1) { bt = __builtin_amdgcn_mfma_f32_16x16x32_bf16(P1, lb[0], cv, 0, 0, 0); bt = __builtin_amdgcn_mfma_f32_16x16x32_bf16(ONES, lb[1], bt, 0, 0, 0); }
;       else if (f == 2) bt = __builtin_amdgcn_mfma_f32_16x16x32_bf16(P0, lb[1], cv, 0, 0, 0);
;       else bt = __builtin_amdgcn_mfma_f32_16x16x32_bf16(P1, lb[1], cv, 0, 0, 0);
; #pragma unroll
;       for (int j = 0; j < 4; ++j) {
;         float w = __builtin_amdgcn_exp2f(e0[f][j] + bt[j]);
;         if (diag) { const int key = kb * 64 + 16 * f + 4 * g4 + j; if (key >= qi) w = 0.f; }
;         wb[f >> 1][(f & 1) * 4 + j] = (short)f2bf(w);
;       }
	v_max_f32_e32 v34, 0, v46
	s_nop 0
	v_xor_b32_e32 v50, 0x80000000, v35
	v_max_f32_e32 v35, 0, v47
	v_pk_add_f32 v[76:77], v[34:35], v[44:45]
	v_mul_f32_e32 v45, 0x3e38aa3b, v43
	v_fma_f32 v107, v40, s44, -v76
	v_mul_f32_e32 v40, 0x3e38aa3b, v42
	v_exp_f32_e64 v35, -|v40|
	v_exp_f32_e64 v44, -|v45|
	s_nop 0
	s_nop 0
	s_nop 0
	s_nop 0
	s_nop 0
	v_xor_b32_e32 v46, 0x80000000, v76
	v_add_f32_e32 v34, 1.0, v35
	v_add_f32_e32 v35, 1.0, v44
	v_log_f32_e32 v34, v34
	v_log_f32_e32 v35, v35
	v_max_f32_e32 v44, 0, v40
	v_max_f32_e32 v45, 0, v45
	s_nop 0
	v_pk_add_f32 v[78:79], v[44:45], v[34:35]
	s_nop 0
	v_xor_b32_e32 v47, 0x80000000, v77
	s_nop 0
	s_nop 0
	s_nop 0
	v_bfe_u32 v75, v50, 16, 1
	s_nop 0
	v_bfe_u32 v76, v51, 16, 1
	v_bfe_u32 v108, v48, 16, 1
	v_bfe_u32 v109, v49, 16, 1
	s_mov_b32 s53, s48
	s_nop 0
	v_xor_b32_e32 v40, 0x80000000, v78
	v_add3_u32 v109, v49, v109, s96
	v_add3_u32 v108, v48, v108, s96
	v_add3_u32 v76, v51, v76, s96
	v_add3_u32 v110, v50, v75, s96
	s_mov_b32 s54, s48
	s_mov_b32 s55, s48
	v_mov_b64_e32 v[48:49], s[52:53]
	v_xor_b32_e32 v44, 0x80000000, v79
	v_mov_b32_e32 v33, v32
	v_mov_b32_e32 v34, v32
	v_mov_b32_e32 v35, v32
	v_bfe_u32 v72, v40, 16, 1
	v_bfe_u32 v73, v47, 16, 1
	v_bfe_u32 v74, v46, 16, 1
	v_mov_b64_e32 v[50:51], s[54:55]
	v_add3_u32 v46, v46, v74, s96
	v_add3_u32 v111, v47, v73, s96
	v_add3_u32 v40, v40, v72, s96
	v_mfma_f32_16x16x32_bf16 v[72:75], v[4:7], v[36:39], v[32:35]
	v_bfe_u32 v45, v44, 16, 1
	v_add3_u32 v44, v44, v45, s96
	v_perm_b32 v47, v44, v40, s45
	v_perm_b32 v46, v111, v46, s45
	v_perm_b32 v45, v110, v76, s45
	v_perm_b32 v44, v108, v109, s45
	v_fma_f32 v76, v42, s44, -v78
	v_readlane_b32 s49, v161, 25
	v_mfma_f32_16x16x32_bf16 v[72:75], v[48:51], v[44:47], v[72:75]
	v_readlane_b32 s50, v161, 26
	v_readlane_b32 s51, v161, 27
	v_writelane_b32 v161, s48, 24
	v_readlane_b32 s60, v160, 9
	v_readlane_b32 s61, v160, 10
	s_nop 2
	v_add_f32_e32 v40, v82, v72
	v_exp_f32_e32 v40, v40
	v_fma_f32 v72, v41, s44, -v77
	v_add_f32_e32 v42, v80, v73
	v_exp_f32_e32 v42, v42
	s_nop 0
	s_nop 0
	v_bfe_u32 v41, v40, 16, 1
	v_add3_u32 v78, v40, v41, s96
	v_add_f32_e32 v41, v81, v74
	v_exp_f32_e32 v41, v41
	s_nop 0
	v_mov_b32_e32 v40, v42
	v_bfe_u32 v42, v40, 16, 1
	v_fma_f32 v77, v43, s44, -v79
	v_add3_u32 v79, v40, v42, s96
	s_nop 0
	v_mov_b32_e32 v73, v41
	v_add_f32_e32 v40, v83, v75
	v_exp_f32_e32 v74, v40
	v_mfma_f32_16x16x32_bf16 v[40:43], v[0:3], v[36:39], v[32:35]
	v_bfe_u32 v75, v73, 16, 1
	v_add3_u32 v80, v73, v75, s96
	s_nop 0
	v_mfma_f32_16x16x32_bf16 v[40:43], v[48:51], v[44:47], v[40:43]
	v_mov_b32_e32 v73, v74
	v_bfe_u32 v74, v73, 16, 1
	v_add3_u32 v81, v73, v74, s96
	s_mov_b32 s0, 0xffff
	v_writelane_b32 v161, s49, 25
	s_nop 2
	v_add_f32_e32 v40, v84, v40
	v_exp_f32_e32 v40, v40
	v_add_f32_e32 v41, v85, v41
	v_exp_f32_e32 v41, v41
	v_add_f32_e32 v42, v86, v42
	s_nop 0
	s_nop 0
	v_bfe_u32 v73, v40, 16, 1
	v_exp_f32_e32 v42, v42
	v_add3_u32 v82, v40, v73, s96
	s_nop 0
	v_mov_b32_e32 v40, v41
	v_bfe_u32 v41, v40, 16, 1
	v_add3_u32 v83, v40, v41, s96
	s_nop 0
	v_add_f32_e32 v41, v87, v43
	v_mov_b32_e32 v40, v42
	v_exp_f32_e32 v73, v41
	v_bfe_u32 v41, v40, 16, 1
	v_add3_u32 v74, v40, v41, s96
	v_mfma_f32_16x16x32_bf16 v[40:43], v[4:7], v[44:47], v[32:35]
	s_nop 0
	s_nop 0
	v_bfe_u32 v75, v73, 16, 1
	v_add3_u32 v73, v73, v75, s96
	v_writelane_b32 v161, s50, 26
	s_nop 2
	v_add_f32_e32 v40, v103, v40
	v_exp_f32_e32 v40, v40
	v_add_f32_e32 v41, v104, v41
	v_exp_f32_e32 v41, v41
	v_add_f32_e32 v42, v105, v42
	s_nop 0
	s_nop 0
	v_bfe_u32 v75, v40, 16, 1
	v_exp_f32_e32 v42, v42
	v_add3_u32 v84, v40, v75, s96
	s_nop 0
	v_mov_b32_e32 v40, v41
	v_bfe_u32 v41, v40, 16, 1
	v_add3_u32 v85, v40, v41, s96
	s_nop 0
	v_add_f32_e32 v41, v106, v43
	v_mov_b32_e32 v40, v42
	v_exp_f32_e32 v75, v41
	v_bfe_u32 v41, v40, 16, 1
	v_add3_u32 v86, v40, v41, s96
	v_mfma_f32_16x16x32_bf16 v[40:43], v[0:3], v[44:47], v[32:35]
	s_nop 0
	s_nop 0
	v_bfe_u32 v87, v75, 16, 1
	v_add3_u32 v87, v75, v87, s96
	v_mfma_f32_16x16x32_bf16 v[32:35], v[48:51], v[36:39], v[32:35]
	s_nop 2
	v_add_f32_e32 v40, v40, v107
	v_exp_f32_e32 v40, v40
	v_add_f32_e32 v41, v41, v72
	v_exp_f32_e32 v41, v41
	v_add_f32_e32 v42, v42, v76
	s_nop 0
	s_nop 0
	v_bfe_u32 v72, v40, 16, 1
	v_add3_u32 v103, v40, v72, s96
	s_nop 0
	v_exp_f32_e32 v42, v42
	v_mov_b32_e32 v40, v41
	v_bfe_u32 v41, v40, 16, 1
	v_add3_u32 v104, v40, v41, s96
	v_add_f32_e32 v41, v43, v77
	s_nop 0
	v_exp_f32_e32 v72, v41
	v_mov_b32_e32 v40, v42
	v_bfe_u32 v41, v40, 16, 1
	v_add_u32_e32 v77, 0x2000, v71
	v_add3_u32 v76, v40, v41, s96
	ds_read2_b64 v[40:43], v77 offset0:128 offset1:132
	s_nop 0
	s_nop 0
	v_bfe_u32 v75, v72, 16, 1
	v_add3_u32 v105, v72, v75, s96
	v_perm_b32 v39, v73, v74, s45
	ds_read2_b64 v[72:75], v77 offset0:136 offset1:140
	s_waitcnt lgkmcnt(1)
; __device__ void sbattn_item(const Params& p, int l, int item, unsigned char* ldsraw) {
;     ...
; #pragma unroll
;     for (int df = 0; df < 4; ++df)
; #pragma unroll
;       for (int k2 = 0; k2 < 2; ++k2) {
;         const u16* vp = Vt + (df * 16 + l15) * KLD + k2 * 32 + 4 * g4;
;         const uint2 lo = *(const uint2*)(vp);
;         const uint2 hi = *(const uint2*)(vp + 16);
;         bf16x8 av;
;         av[0] = (short)(lo.x & 0xffff); av[1] = (short)(lo.x >> 16); av[2] = (short)(lo.y & 0xffff); av[3] = (short)(lo.y >> 16);
;         av[4] = (short)(hi.x & 0xffff); av[5] = (short)(hi.x >> 16); av[6] = (short)(hi.y & 0xffff); av[7] = (short)(hi.y >> 16);
;         ot[df] = __builtin_amdgcn_mfma_f32_16x16x32_bf16(av, wb[k2], ot[df], 0, 0, 0);
;       }
;     carry = tot[0];
	v_bfi_b32 v42, s0, v42, v42
	v_perm_b32 v38, v83, v82, s45
	v_perm_b32 v37, v81, v80, s45
	v_perm_b32 v36, v79, v78, s45
	s_waitcnt lgkmcnt(0)
	v_bfi_b32 v74, s0, v74, v74
	v_add_u32_e32 v80, 0x2800, v71
	v_mfma_f32_16x16x32_bf16 v[20:23], v[40:43], v[36:39], v[20:23]
	v_perm_b32 v43, v105, v76, s45
	ds_read2_b64 v[76:79], v80 offset0:160 offset1:164
	v_perm_b32 v42, v104, v103, s45
	v_perm_b32 v41, v87, v86, s45
	v_perm_b32 v40, v85, v84, s45
	v_mfma_f32_16x16x32_bf16 v[32:35], v[48:51], v[44:47], v[32:35]
	s_waitcnt lgkmcnt(0)
	v_bfi_b32 v78, s0, v78, v78
	v_writelane_b32 v161, s51, 27
	v_readlane_b32 s62, v160, 11
	v_mfma_f32_16x16x32_bf16 v[20:23], v[72:75], v[40:43], v[20:23]
	ds_read2_b64 v[72:75], v80 offset0:168 offset1:172
	v_add_u32_e32 v80, 0x3000, v71
	v_readlane_b32 s24, v161, 44
	v_mfma_f32_16x16x32_bf16 v[16:19], v[76:79], v[36:39], v[16:19]
	ds_read2_b64 v[76:79], v80 offset0:192 offset1:196
	s_waitcnt lgkmcnt(1)
	v_bfi_b32 v74, s0, v74, v74
	v_readlane_b32 s63, v160, 12
	v_readlane_b32 s64, v160, 13
	v_mfma_f32_16x16x32_bf16 v[16:19], v[72:75], v[40:43], v[16:19]
	ds_read2_b64 v[72:75], v80 offset0:200 offset1:204
	s_waitcnt lgkmcnt(1)
	v_bfi_b32 v78, s0, v78, v78
	v_add_u32_e32 v80, 0x3800, v71
	v_readlane_b32 s65, v160, 14
	v_mfma_f32_16x16x32_bf16 v[12:15], v[76:79], v[36:39], v[12:15]
	s_waitcnt lgkmcnt(0)
	v_bfi_b32 v74, s0, v74, v74
	ds_read2_b64 v[76:79], v80 offset0:224 offset1:228
	v_readlane_b32 s66, v160, 15
	v_mfma_f32_16x16x32_bf16 v[12:15], v[72:75], v[40:43], v[12:15]
	ds_read2_b64 v[72:75], v80 offset0:232 offset1:236
	s_waitcnt lgkmcnt(1)
	v_bfi_b32 v78, s0, v78, v78
	v_readlane_b32 s67, v160, 16
	v_readlane_b32 s68, v160, 17
	v_mfma_f32_16x16x32_bf16 v[8:11], v[76:79], v[36:39], v[8:11]
	s_waitcnt lgkmcnt(0)
	v_bfi_b32 v74, s0, v74, v74
	v_readlane_b32 s69, v160, 18
	v_readlane_b32 s70, v160, 19
	v_mfma_f32_16x16x32_bf16 v[8:11], v[72:75], v[40:43], v[8:11]
	v_readlane_b32 s71, v160, 20
	v_readlane_b32 s72, v160, 21
	v_readlane_b32 s73, v160, 22
	v_readlane_b32 s74, v160, 23
	v_readlane_b32 s75, v160, 24
	v_readlane_b32 s25, v161, 45
	v_readlane_b32 s26, v161, 46
	v_readlane_b32 s27, v161, 47
	s_mov_b64 s[36:37], s[46:47]
	s_mov_b64 s[46:47], s[84:85]
	s_mov_b64 s[84:85], s[88:89]
	s_mov_b64 s[88:89], s[4:5]
	s_mov_b64 s[4:5], s[76:77]
	s_mov_b64 s[76:77], s[82:83]
	s_movk_i32 s83, 0x1920
	s_mov_b32 s82, 0x800000
	s_mov_b64 s[34:35], s[58:59]
	s_movk_i32 s40, 0x1000
	s_movk_i32 s41, 0x180
	s_mov_b64 s[44:45], s[56:57]
